# P8 row stores as plain write-back stores instead of nt (testing whether contiguous rows change the best cache policy)
# baseline (speedup 1.0000x reference)
.LBB0_1729:
	s_ashr_i32 s21, s62, 31
	s_lshr_b32 s21, s21, 28
	s_add_i32 s21, s62, s21
	s_ashr_i32 s30, s21, 4
	s_ashr_i32 s31, s30, 31
	s_lshl_b32 s19, s62, 8
	s_lshl_b64 s[40:41], s[30:31], 25
	s_add_u32 s40, s51, s40
	s_addc_u32 s41, s52, s41
	s_lshl_b32 s21, s30, 12
	s_sub_i32 s19, s19, s21
	v_lshl_add_u32 v152, s28, 8, v146
	v_or_b32_e32 v144, s19, v148
	v_ashrrev_i32_e32 v145, 31, v144
	v_ashrrev_i32_e32 v153, 31, v152
	v_lshl_add_u64 v[154:155], v[144:145], 1, s[40:41]
	v_lshlrev_b64 v[144:145], 13, v[152:153]
	v_lshl_add_u64 v[144:145], v[154:155], 0, v[144:145]
	v_cvt_pk_bf16_f32 v124, v124, v125
	v_cvt_pk_bf16_f32 v125, v126, v127
	v_cvt_pk_bf16_f32 v126, v120, v121
	v_cvt_pk_bf16_f32 v127, v122, v123
	ds_write_b128 v224, v[124:127]
	v_cvt_pk_bf16_f32 v112, v112, v113
	v_cvt_pk_bf16_f32 v113, v114, v115
	v_cvt_pk_bf16_f32 v114, v104, v105
	v_or_b32_e32 v104, 16, v152
	v_ashrrev_i32_e32 v105, 31, v104
	v_lshlrev_b64 v[104:105], 13, v[104:105]
	v_cvt_pk_bf16_f32 v115, v106, v107
	ds_write_b128 v224, v[112:115] offset:64
	v_lshl_add_u64 v[226:227], v[144:145], 0, s[98:99]
	s_waitcnt lgkmcnt(0)
	s_barrier
	ds_read_b128 v[228:231], v225
	ds_read_b128 v[232:235], v225 offset:1056
	s_waitcnt lgkmcnt(0)
	s_barrier
	global_store_dwordx4 v[144:145], v[228:231], off
	global_store_dwordx4 v[226:227], v[232:235], off
	s_nop 1
	v_lshl_add_u64 v[112:113], v[154:155], 0, v[104:105]
	v_cvt_pk_bf16_f32 v104, v116, v117
	v_cvt_pk_bf16_f32 v105, v118, v119
	v_cvt_pk_bf16_f32 v106, v108, v109
	v_cvt_pk_bf16_f32 v107, v110, v111
	ds_write_b128 v224, v[104:107]
	v_cvt_pk_bf16_f32 v96, v96, v97
	v_cvt_pk_bf16_f32 v97, v98, v99
	v_cvt_pk_bf16_f32 v98, v88, v89
	v_or_b32_e32 v88, 32, v152
	v_ashrrev_i32_e32 v89, 31, v88
	v_lshlrev_b64 v[88:89], 13, v[88:89]
	v_cvt_pk_bf16_f32 v99, v90, v91
	ds_write_b128 v224, v[96:99] offset:64
	v_lshl_add_u64 v[226:227], v[112:113], 0, s[98:99]
	s_waitcnt lgkmcnt(0)
	s_barrier
	ds_read_b128 v[228:231], v225
	ds_read_b128 v[232:235], v225 offset:1056
	s_waitcnt lgkmcnt(0)
	s_barrier
	global_store_dwordx4 v[112:113], v[228:231], off
	global_store_dwordx4 v[226:227], v[232:235], off
	s_nop 1
	v_lshl_add_u64 v[96:97], v[154:155], 0, v[88:89]
	v_cvt_pk_bf16_f32 v88, v100, v101
	v_cvt_pk_bf16_f32 v89, v102, v103
	v_cvt_pk_bf16_f32 v90, v92, v93
	v_cvt_pk_bf16_f32 v91, v94, v95
	ds_write_b128 v224, v[88:91]
	v_cvt_pk_bf16_f32 v80, v80, v81
	v_cvt_pk_bf16_f32 v81, v82, v83
	v_cvt_pk_bf16_f32 v82, v72, v73
	v_or_b32_e32 v72, 48, v152
	v_ashrrev_i32_e32 v73, 31, v72
	v_lshlrev_b64 v[72:73], 13, v[72:73]
	v_cvt_pk_bf16_f32 v83, v74, v75
	ds_write_b128 v224, v[80:83] offset:64
	v_lshl_add_u64 v[226:227], v[96:97], 0, s[98:99]
	s_waitcnt lgkmcnt(0)
	s_barrier
	ds_read_b128 v[228:231], v225
	ds_read_b128 v[232:235], v225 offset:1056
	s_waitcnt lgkmcnt(0)
	s_barrier
	global_store_dwordx4 v[96:97], v[228:231], off
	global_store_dwordx4 v[226:227], v[232:235], off
	s_nop 1
	v_lshl_add_u64 v[80:81], v[154:155], 0, v[72:73]
	v_cvt_pk_bf16_f32 v72, v84, v85
	v_cvt_pk_bf16_f32 v73, v86, v87
	v_cvt_pk_bf16_f32 v74, v76, v77
	v_cvt_pk_bf16_f32 v75, v78, v79
	ds_write_b128 v224, v[72:75]
	v_cvt_pk_bf16_f32 v68, v68, v69
	v_cvt_pk_bf16_f32 v69, v70, v71
	v_cvt_pk_bf16_f32 v70, v64, v65
	v_cvt_pk_bf16_f32 v71, v66, v67
	ds_write_b128 v224, v[68:71] offset:64
	v_lshl_add_u64 v[226:227], v[80:81], 0, s[98:99]
	s_waitcnt lgkmcnt(0)
	s_barrier
	ds_read_b128 v[228:231], v225
	ds_read_b128 v[232:235], v225 offset:1056
	s_waitcnt lgkmcnt(0)
	s_barrier
	global_store_dwordx4 v[80:81], v[228:231], off
	global_store_dwordx4 v[226:227], v[232:235], off
	v_cvt_pk_bf16_f32 v60, v60, v61
	v_cvt_pk_bf16_f32 v61, v62, v63
	v_cvt_pk_bf16_f32 v62, v56, v57
	v_add_co_u32_e32 v56, vcc, s58, v144
	v_lshl_add_u64 v[64:65], v[144:145], 0, s[10:11]
	s_nop 0
	v_addc_co_u32_e32 v57, vcc, 0, v145, vcc
	v_cvt_pk_bf16_f32 v63, v58, v59
	ds_write_b128 v224, v[60:63]
	v_cvt_pk_bf16_f32 v48, v48, v49
	v_cvt_pk_bf16_f32 v49, v50, v51
	v_cvt_pk_bf16_f32 v50, v40, v41
	v_cvt_pk_bf16_f32 v51, v42, v43
	ds_write_b128 v224, v[48:51] offset:64
	v_lshl_add_u64 v[226:227], v[64:65], 0, s[98:99]
	s_waitcnt lgkmcnt(0)
	s_barrier
	ds_read_b128 v[228:231], v225
	ds_read_b128 v[232:235], v225 offset:1056
	s_waitcnt lgkmcnt(0)
	s_barrier
	global_store_dwordx4 v[56:57], v[228:231], off
	global_store_dwordx4 v[226:227], v[232:235], off
	v_cvt_pk_bf16_f32 v40, v52, v53
	v_cvt_pk_bf16_f32 v41, v54, v55
	v_cvt_pk_bf16_f32 v42, v44, v45
	v_add_co_u32_e32 v44, vcc, s59, v144
	s_nop 0
	v_lshl_add_u64 v[48:49], v[144:145], 0, s[12:13]
	v_addc_co_u32_e32 v45, vcc, 0, v145, vcc
	v_cvt_pk_bf16_f32 v43, v46, v47
	ds_write_b128 v224, v[40:43]
	v_cvt_pk_bf16_f32 v32, v32, v33
	v_cvt_pk_bf16_f32 v33, v34, v35
	v_cvt_pk_bf16_f32 v34, v24, v25
	v_cvt_pk_bf16_f32 v35, v26, v27
	ds_write_b128 v224, v[32:35] offset:64
	v_lshl_add_u64 v[226:227], v[48:49], 0, s[98:99]
	s_waitcnt lgkmcnt(0)
	s_barrier
	ds_read_b128 v[228:231], v225
	ds_read_b128 v[232:235], v225 offset:1056
	s_waitcnt lgkmcnt(0)
	s_barrier
	global_store_dwordx4 v[44:45], v[228:231], off
	global_store_dwordx4 v[226:227], v[232:235], off
	v_cvt_pk_bf16_f32 v24, v36, v37
	v_cvt_pk_bf16_f32 v25, v38, v39
	v_cvt_pk_bf16_f32 v26, v28, v29
	v_add_co_u32_e32 v28, vcc, s60, v144
	s_nop 0
	v_lshl_add_u64 v[32:33], v[144:145], 0, s[14:15]
	v_addc_co_u32_e32 v29, vcc, 0, v145, vcc
	v_cvt_pk_bf16_f32 v27, v30, v31
	ds_write_b128 v224, v[24:27]
	v_cvt_pk_bf16_f32 v16, v16, v17
	v_cvt_pk_bf16_f32 v17, v18, v19
	v_cvt_pk_bf16_f32 v18, v8, v9
	v_cvt_pk_bf16_f32 v19, v10, v11
	ds_write_b128 v224, v[16:19] offset:64
	v_lshl_add_u64 v[226:227], v[32:33], 0, s[98:99]
	s_waitcnt lgkmcnt(0)
	s_barrier
	ds_read_b128 v[228:231], v225
	ds_read_b128 v[232:235], v225 offset:1056
	s_waitcnt lgkmcnt(0)
	s_barrier
	global_store_dwordx4 v[28:29], v[228:231], off
	global_store_dwordx4 v[226:227], v[232:235], off
	v_cvt_pk_bf16_f32 v8, v20, v21
	v_cvt_pk_bf16_f32 v9, v22, v23
	v_cvt_pk_bf16_f32 v10, v12, v13
	v_add_co_u32_e32 v12, vcc, s61, v144
	s_nop 0
	v_lshl_add_u64 v[16:17], v[144:145], 0, s[16:17]
	v_addc_co_u32_e32 v13, vcc, 0, v145, vcc
	s_andn2_b64 vcc, exec, s[0:1]
	s_mov_b64 s[0:1], -1
	v_cvt_pk_bf16_f32 v11, v14, v15
	ds_write_b128 v224, v[8:11]
	v_cvt_pk_bf16_f32 v4, v4, v5
	v_cvt_pk_bf16_f32 v5, v6, v7
	v_cvt_pk_bf16_f32 v6, v0, v1
	v_cvt_pk_bf16_f32 v7, v2, v3
	ds_write_b128 v224, v[4:7] offset:64
	v_lshl_add_u64 v[226:227], v[16:17], 0, s[98:99]
	s_waitcnt lgkmcnt(0)
	s_barrier
	ds_read_b128 v[228:231], v225
	ds_read_b128 v[232:235], v225 offset:1056
	s_waitcnt lgkmcnt(0)
	s_barrier
	global_store_dwordx4 v[12:13], v[228:231], off
	global_store_dwordx4 v[226:227], v[232:235], off
	s_cbranch_vccnz .LBB0_1718
	s_andn2_b64 vcc, exec, s[4:5]
	s_cbranch_vccnz .LBB0_1717
	s_barrier
	s_branch .LBB0_1717
